# GEMM k-loop: counted lgkmcnt ladder so MFMAs start after 5 of 12 fragment reads; phase-0 grid sync replaced by XCD-hierarchical barrier copy
# speedup vs baseline: 1.0041x; 1.0041x over previous
; __device__ __forceinline__ unsigned xb_ld(unsigned* p)              { return __hip_atomic_load(p, __ATOMIC_RELAXED, __HIP_MEMORY_SCOPE_AGENT); }
; __device__ __forceinline__ unsigned xb_add(unsigned* p, unsigned v) { return __hip_atomic_fetch_add(p, v, __ATOMIC_RELAXED, __HIP_MEMORY_SCOPE_AGENT); }
; __device__ __forceinline__ void xcd_barrier_complete(unsigned* bar, unsigned x, unsigned& nloc, unsigned& nx) {
;   const unsigned G = gridDim.x * gridDim.y * gridDim.z;
;   unsigned sum, cnt, mine, sp = 0u;
;   for (;;) {
;     sum = 0u; cnt = 0u; mine = 0u;
; #pragma unroll
;     for (unsigned j = 0; j < 16; ++j) { const unsigned c = xb_ld(&bar[XB_XCNT(j)]); sum += c; cnt += (c > 0u) ? 1u : 0u; mine = (j == x) ? c : mine; }
;     if (sum == G) break;
; __device__ __forceinline__ void xcd_barrier(const XcdBarrier& b) {
;   asm volatile("s_waitcnt vmcnt(0)" ::: "memory");
;   __syncthreads();
;   if (__builtin_amdgcn_workitem_id_x() == 0) {
;     unsigned* bar = b.bar;
;     __builtin_amdgcn_s_waitcnt(0);
;     unsigned nloc = b.st[0], nx = b.st[1];
;     if (nloc == 0u) { xcd_barrier_complete(bar, b.x, nloc, nx); b.st[0] = nloc; b.st[1] = nx; }
;     const unsigned old = xb_add(&bar[XB_XSUB(b.x)], 1u);
.LBB0_72:
	v_writelane_b32 v245, s14, 0
	v_writelane_b32 v245, s15, 1
	v_writelane_b32 v245, s24, 2
	v_writelane_b32 v245, s25, 3
	v_writelane_b32 v245, s26, 4
	v_writelane_b32 v245, s27, 5
	v_writelane_b32 v245, s29, 6
	v_writelane_b32 v245, s30, 7
	v_writelane_b32 v245, s31, 8
	v_writelane_b32 v245, s56, 9
	v_writelane_b32 v245, s57, 10
	v_writelane_b32 v245, s58, 11
	v_writelane_b32 v245, s59, 12
	v_writelane_b32 v245, s6, 13
	v_writelane_b32 v245, s64, 14
	v_writelane_b32 v245, s83, 15
	v_writelane_b32 v245, s84, 16
	v_writelane_b32 v245, s86, 17
	s_waitcnt vmcnt(0)
	s_waitcnt lgkmcnt(0)
	s_barrier
	s_mov_b64 s[0:1], exec
	v_readlane_b32 s2, v244, 4
	v_readlane_b32 s3, v244, 5
	s_and_b64 s[2:3], s[0:1], s[2:3]
	s_mov_b64 exec, s[2:3]
	s_cbranch_execz .LBB0_165_c
	v_mov_b32_e32 v0, 0x12000
	s_waitcnt vmcnt(0) expcnt(0) lgkmcnt(0)
	ds_read_b32 v2, v0
	v_mov_b32_e32 v0, 0x12004
	ds_read_b32 v0, v0
	s_waitcnt lgkmcnt(1)
	v_cmp_ne_u32_e32 vcc, 0, v2
	s_cbranch_vccnz .LBB0_129_c
	v_readlane_b32 s4, v244, 2
	v_readlane_b32 s5, v244, 3
	s_load_dwordx2 s[2:3], s[4:5], 0x4
	s_add_u32 s4, s76, 0x1f1b6200
	s_addc_u32 s5, s77, 0
	s_add_u32 s6, s76, 0x1f1b6400
	s_addc_u32 s7, s77, 0
	s_add_u32 s8, s76, 0x1f1b6500
	s_addc_u32 s9, s77, 0
	s_add_u32 s10, s76, 0x1f1b6600
	s_addc_u32 s11, s77, 0
	s_add_u32 s12, s76, 0x1f1b6700
	s_addc_u32 s13, s77, 0
	s_add_u32 s14, s76, 0x1f1b6800
	s_addc_u32 s15, s77, 0
	s_add_u32 s24, s76, 0x1f1b6900
	s_addc_u32 s25, s77, 0
	s_add_u32 s26, s76, 0x1f1b6a00
	s_addc_u32 s27, s77, 0
	s_add_u32 s30, s76, 0x1f1b6b00
	s_addc_u32 s31, s77, 0
	s_add_u32 s56, s76, 0x1f1b6c00
	s_addc_u32 s57, s77, 0
	s_add_u32 s58, s76, 0x1f1b6d00
	s_addc_u32 s59, s77, 0
	s_add_u32 s64, s76, 0x1f1b6e00
	s_addc_u32 s65, s77, 0
	s_add_u32 s66, s76, 0x1f1b6f00
	s_addc_u32 s67, s77, 0
	s_add_u32 s80, s76, 0x1f1b7000
	s_addc_u32 s81, s77, 0
	s_add_u32 s82, s76, 0x1f1b7100
	s_addc_u32 s83, s77, 0
	s_add_u32 s84, s76, 0x1f1b7200
	s_addc_u32 s85, s77, 0
	s_waitcnt lgkmcnt(0)
	s_mul_i32 s2, s2, s34
	s_add_u32 s86, s76, 0x1f1b7300
	s_mul_i32 s2, s2, s3
	s_addc_u32 s87, s77, 0
	s_mov_b32 s3, 1
	v_mov_b32_e32 v16, 0
	s_branch .LBB0_117_c

; __device__ __forceinline__ void xcd_barrier(const XcdBarrier& b) {
;     ...
;   __syncthreads();
; }
.Lxb0_end:
	v_readlane_b32 s14, v245, 0
	v_readlane_b32 s15, v245, 1
	v_readlane_b32 s24, v245, 2
	v_readlane_b32 s25, v245, 3
	v_readlane_b32 s26, v245, 4
	v_readlane_b32 s27, v245, 5
	v_readlane_b32 s29, v245, 6
	v_readlane_b32 s30, v245, 7
	v_readlane_b32 s31, v245, 8
	v_readlane_b32 s56, v245, 9
	v_readlane_b32 s57, v245, 10
	v_readlane_b32 s58, v245, 11
	v_readlane_b32 s59, v245, 12
	v_readlane_b32 s6, v245, 13
	v_readlane_b32 s64, v245, 14
	v_readlane_b32 s83, v245, 15
	v_readlane_b32 s84, v245, 16
	v_readlane_b32 s86, v245, 17

; __global__ void __launch_bounds__(256, 2) mega(Params p) {
;   __shared__ __attribute__((aligned(16))) char smem[SMEM_BYTES];
	.amdhsa_kernel _Z4mega6Params
		.amdhsa_group_segment_fixed_size 73744
		.amdhsa_private_segment_fixed_size 0
		.amdhsa_kernarg_size 496
		.amdhsa_user_sgpr_count 2
		.amdhsa_user_sgpr_dispatch_ptr 0
		.amdhsa_user_sgpr_queue_ptr 0
		.amdhsa_user_sgpr_kernarg_segment_ptr 1
		.amdhsa_user_sgpr_dispatch_id 0
		.amdhsa_user_sgpr_kernarg_preload_length 0
		.amdhsa_user_sgpr_kernarg_preload_offset 0
		.amdhsa_user_sgpr_private_segment_size 0
		.amdhsa_uses_dynamic_stack 0
		.amdhsa_enable_private_segment 0
		.amdhsa_system_sgpr_workgroup_id_x 1
		.amdhsa_system_sgpr_workgroup_id_y 0
		.amdhsa_system_sgpr_workgroup_id_z 0
		.amdhsa_system_sgpr_workgroup_info 0
		.amdhsa_system_vgpr_workitem_id 2
		.amdhsa_next_free_vgpr 256
		.amdhsa_next_free_sgpr 98
		.amdhsa_accum_offset 256
		.amdhsa_reserve_vcc 1
		.amdhsa_float_round_mode_32 0
		.amdhsa_float_round_mode_16_64 0
		.amdhsa_float_denorm_mode_32 3
		.amdhsa_float_denorm_mode_16_64 3
		.amdhsa_dx10_clamp 1
		.amdhsa_ieee_mode 1
		.amdhsa_fp16_overflow 0
		.amdhsa_tg_split 0
		.amdhsa_exception_fp_ieee_invalid_op 0
		.amdhsa_exception_fp_denorm_src 0
		.amdhsa_exception_fp_ieee_div_zero 0
		.amdhsa_exception_fp_ieee_overflow 0
		.amdhsa_exception_fp_ieee_underflow 0
		.amdhsa_exception_fp_ieee_inexact 0
		.amdhsa_exception_int_div_zero 0
	.end_amdhsa_kernel

; __global__ void __launch_bounds__(256, 2) mega(Params p) {
;   __shared__ __attribute__((aligned(16))) char smem[SMEM_BYTES];
amdhsa.kernels:
  - .agpr_count:     0
    .args:
      - .offset:         0
        .size:           240
        .value_kind:     by_value
      - .offset:         240
        .size:           4
        .value_kind:     hidden_block_count_x
      - .offset:         244
        .size:           4
        .value_kind:     hidden_block_count_y
      - .offset:         248
        .size:           4
        .value_kind:     hidden_block_count_z
      - .offset:         252
        .size:           2
        .value_kind:     hidden_group_size_x
      - .offset:         254
        .size:           2
        .value_kind:     hidden_group_size_y
      - .offset:         256
        .size:           2
        .value_kind:     hidden_group_size_z
      - .offset:         258
        .size:           2
        .value_kind:     hidden_remainder_x
      - .offset:         260
        .size:           2
        .value_kind:     hidden_remainder_y
      - .offset:         262
        .size:           2
        .value_kind:     hidden_remainder_z
      - .offset:         280
        .size:           8
        .value_kind:     hidden_global_offset_x
      - .offset:         288
        .size:           8
        .value_kind:     hidden_global_offset_y
      - .offset:         296
        .size:           8
        .value_kind:     hidden_global_offset_z
      - .offset:         304
        .size:           2
        .value_kind:     hidden_grid_dims
      - .offset:         328
        .size:           8
        .value_kind:     hidden_multigrid_sync_arg
    .group_segment_fixed_size: 73744
    .kernarg_segment_align: 8
    .kernarg_segment_size: 496
    .language:       OpenCL C
    .language_version:
      - 2
      - 0
    .max_flat_workgroup_size: 256
    .name:           _Z4mega6Params
    .private_segment_fixed_size: 0
    .sgpr_count:     104
    .sgpr_spill_count: 91
    .symbol:         _Z4mega6Params.kd
    .uniform_work_group_size: 1
    .uses_dynamic_stack: false
    .vgpr_count:     256
    .vgpr_spill_count: 0
    .wavefront_size: 64
